# D1+A2 plus B1: PV waves wait each V fragment pair at its consuming MFMA (counted lgkmcnt(6)) instead of lgkmcnt(0) per 4-MFMA group
# baseline (speedup 1.0000x reference)
; #define A2_WRITET(buf) do { char* kd_ = lds + L_K + (buf) * SHM_K; char* vd_ = lds + L_V + (buf) * 2 * SHM_V; \
;         *(bf16x8*)(kd_ + kws) = sk0; *(bf16x8*)(kd_ + kws + 32 * 256) = sk1; *(bf16x8*)(vd_ + vst0) = sv00; *(bf16x8*)(vd_ + vst1) = sv01; *(bf16x8*)(vd_ + SHM_V + vst0) = sv10; *(bf16x8*)(vd_ + SHM_V + vst1) = sv11; } while (0)
; template <int VB>
; __device__ __forceinline__ void pv_tile(f32x16* o, int vb0, bf16x8 pa0, bf16x8 pa1, bf16x8 pa2, bf16x8 pa3) {
;     ...
;     PV_D0(0); PV_D0(1); PV_D0(2); PV_D0(3);
; __device__ __forceinline__ void attn2_block(const Blk& c, char* lds) {
;     ...
;                 const char* pr = Pb + par * 4096 + lane * 16;
;                 const bf16x8 pa0 = *(const bf16x8*)(pr), pa1 = *(const bf16x8*)(pr + 1024), pa2 = *(const bf16x8*)(pr + 2048), pa3 = *(const bf16x8*)(pr + 3072);
;                 const int vb = vbase + par * 2 * SHM_V;
;                 att::pv_tile<0>(o, vb, pa0, pa1, pa2, pa3);
;                 att::pv_tile<0>(o + 4, vb + SHM_V, pa0, pa1, pa2, pa3);
;             }
;             __syncthreads();
;             if (s + 1 < NT) { asm volatile("s_waitcnt vmcnt(0)" ::: "memory"); A2_WRITET((s + 1) & 1); }
;             __syncthreads();
.LBB0_548:
	v_lshl_add_u32 v2, s85, 12, v230
	ds_read_b128 v[192:195], v2
	ds_read_b128 v[188:191], v2 offset:1024
	ds_read_b128 v[184:187], v2 offset:2048
	ds_read_b128 v[180:183], v2 offset:3072
	v_lshl_add_u32 v2, s85, 15, v231
	ds_read_b64_tr_b16 v[232:233], v2 offset:0
	ds_read_b64_tr_b16 v[234:235], v2 offset:0x800
	ds_read_b64_tr_b16 v[242:243], v2 offset:0x1000
	ds_read_b64_tr_b16 v[244:245], v2 offset:0x1800
	ds_read_b64_tr_b16 v[246:247], v2 offset:0x2000
	ds_read_b64_tr_b16 v[248:249], v2 offset:0x2800
	ds_read_b64_tr_b16 v[250:251], v2 offset:0x3000
	ds_read_b64_tr_b16 v[252:253], v2 offset:0x3800
	s_waitcnt lgkmcnt(6)
	s_waitcnt lgkmcnt(6)
	v_mfma_f32_32x32x16_bf16 v[116:131], v[192:195], v[232:235], v[116:131]
	ds_read_b64_tr_b16 v[232:233], v2 offset:0x200
	ds_read_b64_tr_b16 v[234:235], v2 offset:0xa00
	s_waitcnt lgkmcnt(6)
	v_mfma_f32_32x32x16_bf16 v[116:131], v[188:191], v[242:245], v[116:131]
	ds_read_b64_tr_b16 v[242:243], v2 offset:0x1200
	ds_read_b64_tr_b16 v[244:245], v2 offset:0x1a00
	s_waitcnt lgkmcnt(6)
	v_mfma_f32_32x32x16_bf16 v[116:131], v[184:187], v[246:249], v[116:131]
	ds_read_b64_tr_b16 v[246:247], v2 offset:0x2200
	ds_read_b64_tr_b16 v[248:249], v2 offset:0x2a00
	s_waitcnt lgkmcnt(6)
	v_mfma_f32_32x32x16_bf16 v[116:131], v[180:183], v[250:253], v[116:131]
	ds_read_b64_tr_b16 v[250:251], v2 offset:0x3200
	ds_read_b64_tr_b16 v[252:253], v2 offset:0x3a00
	s_waitcnt lgkmcnt(6)
	v_mfma_f32_32x32x16_bf16 v[100:115], v[192:195], v[232:235], v[100:115]
	ds_read_b64_tr_b16 v[232:233], v2 offset:0x400
	ds_read_b64_tr_b16 v[234:235], v2 offset:0xc00
	s_waitcnt lgkmcnt(6)
	v_mfma_f32_32x32x16_bf16 v[100:115], v[188:191], v[242:245], v[100:115]
	ds_read_b64_tr_b16 v[242:243], v2 offset:0x1400
	ds_read_b64_tr_b16 v[244:245], v2 offset:0x1c00
	s_waitcnt lgkmcnt(6)
	v_mfma_f32_32x32x16_bf16 v[100:115], v[184:187], v[246:249], v[100:115]
	ds_read_b64_tr_b16 v[246:247], v2 offset:0x2400
	ds_read_b64_tr_b16 v[248:249], v2 offset:0x2c00
	s_waitcnt lgkmcnt(6)
	v_mfma_f32_32x32x16_bf16 v[100:115], v[180:183], v[250:253], v[100:115]
	ds_read_b64_tr_b16 v[250:251], v2 offset:0x3400
	ds_read_b64_tr_b16 v[252:253], v2 offset:0x3c00
	s_waitcnt lgkmcnt(6)
	v_mfma_f32_32x32x16_bf16 v[84:99], v[192:195], v[232:235], v[84:99]
	ds_read_b64_tr_b16 v[232:233], v2 offset:0x600
	ds_read_b64_tr_b16 v[234:235], v2 offset:0xe00
	s_waitcnt lgkmcnt(6)
	v_mfma_f32_32x32x16_bf16 v[84:99], v[188:191], v[242:245], v[84:99]
	ds_read_b64_tr_b16 v[242:243], v2 offset:0x1600
	ds_read_b64_tr_b16 v[244:245], v2 offset:0x1e00
	s_waitcnt lgkmcnt(6)
	v_mfma_f32_32x32x16_bf16 v[84:99], v[184:187], v[246:249], v[84:99]
	ds_read_b64_tr_b16 v[246:247], v2 offset:0x2600
	ds_read_b64_tr_b16 v[248:249], v2 offset:0x2e00
	s_waitcnt lgkmcnt(6)
	v_mfma_f32_32x32x16_bf16 v[84:99], v[180:183], v[250:253], v[84:99]
	ds_read_b64_tr_b16 v[250:251], v2 offset:0x3600
	ds_read_b64_tr_b16 v[252:253], v2 offset:0x3e00
	s_waitcnt lgkmcnt(6)
	v_mfma_f32_32x32x16_bf16 v[68:83], v[192:195], v[232:235], v[68:83]
	v_add_u32_e32 v2, 0x4000, v2
	ds_read_b64_tr_b16 v[232:233], v2 offset:0
	ds_read_b64_tr_b16 v[234:235], v2 offset:0x800
	s_waitcnt lgkmcnt(6)
	v_mfma_f32_32x32x16_bf16 v[68:83], v[188:191], v[242:245], v[68:83]
	ds_read_b64_tr_b16 v[242:243], v2 offset:0x1000
	ds_read_b64_tr_b16 v[244:245], v2 offset:0x1800
	s_waitcnt lgkmcnt(6)
	v_mfma_f32_32x32x16_bf16 v[68:83], v[184:187], v[246:249], v[68:83]
	ds_read_b64_tr_b16 v[246:247], v2 offset:0x2000
	ds_read_b64_tr_b16 v[248:249], v2 offset:0x2800
	s_waitcnt lgkmcnt(6)
	v_mfma_f32_32x32x16_bf16 v[68:83], v[180:183], v[250:253], v[68:83]
	ds_read_b64_tr_b16 v[250:251], v2 offset:0x3000
	ds_read_b64_tr_b16 v[252:253], v2 offset:0x3800
	s_waitcnt lgkmcnt(6)
	v_mfma_f32_32x32x16_bf16 v[52:67], v[192:195], v[232:235], v[52:67]
	ds_read_b64_tr_b16 v[232:233], v2 offset:0x200
	ds_read_b64_tr_b16 v[234:235], v2 offset:0xa00
	s_waitcnt lgkmcnt(6)
	v_mfma_f32_32x32x16_bf16 v[52:67], v[188:191], v[242:245], v[52:67]
	ds_read_b64_tr_b16 v[242:243], v2 offset:0x1200
	ds_read_b64_tr_b16 v[244:245], v2 offset:0x1a00
	s_waitcnt lgkmcnt(6)
	v_mfma_f32_32x32x16_bf16 v[52:67], v[184:187], v[246:249], v[52:67]
	ds_read_b64_tr_b16 v[246:247], v2 offset:0x2200
	ds_read_b64_tr_b16 v[248:249], v2 offset:0x2a00
	s_waitcnt lgkmcnt(6)
	v_mfma_f32_32x32x16_bf16 v[52:67], v[180:183], v[250:253], v[52:67]
	ds_read_b64_tr_b16 v[250:251], v2 offset:0x3200
	ds_read_b64_tr_b16 v[252:253], v2 offset:0x3a00
	s_waitcnt lgkmcnt(6)
	v_mfma_f32_32x32x16_bf16 v[36:51], v[192:195], v[232:235], v[36:51]
	ds_read_b64_tr_b16 v[232:233], v2 offset:0x400
	ds_read_b64_tr_b16 v[234:235], v2 offset:0xc00
	s_waitcnt lgkmcnt(6)
	v_mfma_f32_32x32x16_bf16 v[36:51], v[188:191], v[242:245], v[36:51]
	ds_read_b64_tr_b16 v[242:243], v2 offset:0x1400
	ds_read_b64_tr_b16 v[244:245], v2 offset:0x1c00
	s_waitcnt lgkmcnt(6)
	v_mfma_f32_32x32x16_bf16 v[36:51], v[184:187], v[246:249], v[36:51]
	ds_read_b64_tr_b16 v[246:247], v2 offset:0x2400
	ds_read_b64_tr_b16 v[248:249], v2 offset:0x2c00
	s_waitcnt lgkmcnt(6)
	v_mfma_f32_32x32x16_bf16 v[36:51], v[180:183], v[250:253], v[36:51]
	ds_read_b64_tr_b16 v[250:251], v2 offset:0x3400
	ds_read_b64_tr_b16 v[252:253], v2 offset:0x3c00
	s_waitcnt lgkmcnt(6)
	v_mfma_f32_32x32x16_bf16 v[20:35], v[192:195], v[232:235], v[20:35]
	ds_read_b64_tr_b16 v[232:233], v2 offset:0x600
	ds_read_b64_tr_b16 v[234:235], v2 offset:0xe00
	s_waitcnt lgkmcnt(6)
	v_mfma_f32_32x32x16_bf16 v[20:35], v[188:191], v[242:245], v[20:35]
	ds_read_b64_tr_b16 v[242:243], v2 offset:0x1600
	ds_read_b64_tr_b16 v[244:245], v2 offset:0x1e00
	s_waitcnt lgkmcnt(6)
	v_mfma_f32_32x32x16_bf16 v[20:35], v[184:187], v[246:249], v[20:35]
	ds_read_b64_tr_b16 v[246:247], v2 offset:0x2600
	ds_read_b64_tr_b16 v[248:249], v2 offset:0x2e00
	s_waitcnt lgkmcnt(6)
	v_mfma_f32_32x32x16_bf16 v[20:35], v[180:183], v[250:253], v[20:35]
	ds_read_b64_tr_b16 v[250:251], v2 offset:0x3600
	ds_read_b64_tr_b16 v[252:253], v2 offset:0x3e00
	s_waitcnt lgkmcnt(0)
	v_mfma_f32_32x32x16_bf16 v[4:19], v[192:195], v[232:235], v[4:19]
	s_waitcnt vmcnt(0)
	s_barrier
	v_mfma_f32_32x32x16_bf16 v[4:19], v[188:191], v[242:245], v[4:19]
	v_mfma_f32_32x32x16_bf16 v[4:19], v[184:187], v[246:249], v[4:19]
	v_mfma_f32_32x32x16_bf16 v[4:19], v[180:183], v[250:253], v[4:19]
	s_branch .LBB0_543
